# grid barrier: XCD-local release (no L2 writeback, no cross-XCC hop) after steps whose consumers only read tiles produced on the same XCD; enabled only if every blockIdx%8 group sits on one XCC, else a
# speedup vs baseline: 1.0065x; 1.0065x over previous
; #define LAS __attribute__((address_space(3)))
; __device__ __forceinline__ unsigned xb_add(unsigned* p, unsigned v) { return __hip_atomic_fetch_add(p, v, __ATOMIC_RELAXED, __HIP_MEMORY_SCOPE_AGENT); }
; __device__ __forceinline__ unsigned xb_xcc_id() { return (unsigned)__builtin_amdgcn_s_getreg((3 << 11) | 20) & 0xFu; }
; __device__ __forceinline__ XcdBarrier xcd_barrier_post(unsigned* bar, volatile LAS unsigned* st) {
;     XcdBarrier b; b.bar = bar; b.x = xb_xcc_id(); b.st = st;
;     if (threadIdx.x == 0) (void)xb_add(&bar[XB_XCNT(b.x)], 1u);
;     return b;
; __global__ void __launch_bounds__(512) mk_fwd(Params p) {
;     extern __shared__ __attribute__((aligned(16))) unsigned char lds_raw[];
;     LAS unsigned char* lds = (LAS unsigned char*)lds_raw;
;     cg::grid_group grid = cg::this_grid();
;     volatile LAS unsigned* bst = (volatile LAS unsigned*)(lds + 131072);
;     if (threadIdx.x < 4) bst[threadIdx.x] = 0u;
;     __syncthreads();
;     const XcdBarrier bar = xcd_barrier_post((unsigned*)(p.ws + B_BAR), bst);
_Z6mk_fwd6Params:
	s_load_dwordx8 s[24:31], s[0:1], 0x80
	s_mov_b32 s33, s2
	s_add_u32 s2, s0, 0x98
	s_addc_u32 s3, s1, 0
	v_and_b32_e32 v228, 0x3ff, v0
	v_writelane_b32 v252, s2, 0
	v_cmp_gt_u32_e32 vcc, 4, v228
	s_nop 0
	v_writelane_b32 v252, s3, 1
	s_and_saveexec_b64 s[2:3], vcc
	v_lshl_add_u32 v1, v228, 2, 0
	v_add_u32_e32 v1, 0x20000, v1
	v_mov_b32_e32 v2, 0
	ds_write_b32 v1, v2
	s_or_b64 exec, exec, s[2:3]
	s_waitcnt lgkmcnt(0)
	s_barrier
	s_add_u32 s4, s26, 0x1bf00000
	s_getreg_b32 s2, hwreg(HW_REG_XCC_ID, 0, 4)
	s_addc_u32 s5, s27, 0
	s_and_b32 s8, s2, 15
	v_cmp_eq_u32_e64 s[6:7], 0, v228
	s_mov_b64 s[2:3], exec
	s_nop 0
	v_writelane_b32 v252, s6, 2
	s_nop 1
	v_writelane_b32 v252, s7, 3
	s_and_b64 s[6:7], s[2:3], s[6:7]
	s_mov_b64 exec, s[6:7]
	s_cbranch_execz .LBB0_5
	s_mov_b64 s[6:7], exec
	v_mbcnt_lo_u32_b32 v1, s6, 0
	v_mbcnt_hi_u32_b32 v1, s7, v1
	v_cmp_eq_u32_e32 vcc, 0, v1
	s_and_b64 s[10:11], exec, vcc
	s_mov_b64 exec, s[10:11]
	s_cbranch_execz .LBB0_5
	s_lshl_b32 s9, s8, 8
	s_bcnt1_i32_b64 s6, s[6:7]
	v_mov_b32_e32 v1, s9
	v_mov_b32_e32 v2, s6
	global_atomic_add v1, v2, s[4:5] offset:1024
	s_and_b32 s9, s33, 7
	s_lshl_b32 s9, s9, 8
	s_add_i32 s9, s9, 0x3800
	s_lshl_b32 s6, 1, s8
	v_mov_b32_e32 v3, s9
	v_mov_b32_e32 v4, s6
	global_atomic_or v3, v4, s[4:5]

; __device__ __forceinline__ unsigned xb_ld(unsigned* p)              { return __hip_atomic_load(p, __ATOMIC_RELAXED, __HIP_MEMORY_SCOPE_AGENT); }
; __device__ __forceinline__ unsigned xb_add(unsigned* p, unsigned v) { return __hip_atomic_fetch_add(p, v, __ATOMIC_RELAXED, __HIP_MEMORY_SCOPE_AGENT); }
; #define XB_SPIN(cond, bar) do { unsigned _sp = 0; while (cond) { __builtin_amdgcn_s_sleep(1); \
;     if ((++_sp & 255u) == 0u) { if (xb_ld(&(bar)[XB_TMO])) break; if (_sp > XB_SPIN_CAP) { atomicAdd(&(bar)[XB_TMO], 1u); break; } } } } while (0)
; __device__ __forceinline__ void xcd_barrier(const XcdBarrier& b) {
;     asm volatile("s_waitcnt vmcnt(0)" ::: "memory");
;     __syncthreads();
;     if (threadIdx.x == 0) {
;         unsigned* bar = b.bar;
;         __builtin_amdgcn_s_waitcnt(0);
;         unsigned nloc = b.st[0], nx = b.st[1];
;         if (nloc == 0u) { xcd_barrier_complete(bar, b.x, nloc, nx); b.st[0] = nloc; b.st[1] = nx; }
;         const unsigned old = xb_add(&bar[XB_XSUB(b.x)], 1u);
;         const unsigned gen = old / nloc;
;         if (old + 1u == (gen + 1u) * nloc) {
;             __builtin_amdgcn_fence(__ATOMIC_RELEASE, "agent");
;             asm volatile("s_waitcnt vmcnt(0)" ::: "memory");
;             const unsigned og = xb_add(&bar[XB_TOP], 1u);
;             const unsigned tg = og / nx;
;             if (og + 1u == (tg + 1u) * nx) xb_add(&bar[XB_TOPGEN], 1u);
;             else XB_SPIN(xb_ld(&bar[XB_TOPGEN]) == tg, bar);
;             __builtin_amdgcn_fence(__ATOMIC_ACQUIRE, "agent");
;             xb_add(&bar[XB_XGEN(b.x)], 1u);
;             asm volatile("s_waitcnt vmcnt(0)" ::: "memory");
;         } else {
;             XB_SPIN(xb_ld(&bar[XB_XGEN(b.x)]) == gen, bar);
;             __builtin_amdgcn_fence(__ATOMIC_ACQUIRE, "agent");
;             asm volatile("s_waitcnt vmcnt(0)" ::: "memory");
;         }
;     }
;     __syncthreads();
; }
.LBB0_735:
	s_andn2_saveexec_b64 s[4:5], s[4:5]
	s_cbranch_execz .LBB0_755
	s_mov_b64 s[4:5], exec
	s_add_i32 s100, s28, -2
	s_and_b32 s101, s100, 7
	s_cmp_lt_u32 s100, 31
	s_cselect_b32 s100, 1, 0
	s_lshl_b32 s101, 1, s101
	s_and_b32 s101, s101, 0x73
	s_cmp_lg_u32 s101, 0
	s_cselect_b32 s101, 1, 0
	s_and_b32 s100, s100, s101
	s_cmp_eq_u32 s100, 0
	s_cbranch_scc1 .Lbar_global
	v_mov_b32_e32 v1, 0x20008
	ds_read_b32 v2, v1
	s_waitcnt lgkmcnt(0)
	v_readfirstlane_b32 s101, v2
	s_cmp_lg_u32 s101, 0
	s_cbranch_scc1 .Lbar_have_flag
	v_readlane_b32 s10, v253, 48
	v_readlane_b32 s11, v253, 49
	s_nop 4
	global_load_dword v2, v197, s[10:11] offset:1024 sc1
	global_load_dword v3, v197, s[10:11] offset:1280 sc1
	global_load_dword v4, v197, s[10:11] offset:1536 sc1
	global_load_dword v5, v197, s[10:11] offset:1792 sc1
	global_load_dword v6, v197, s[10:11] offset:2048 sc1
	global_load_dword v7, v197, s[10:11] offset:2304 sc1
	global_load_dword v8, v197, s[10:11] offset:2560 sc1
	global_load_dword v9, v197, s[10:11] offset:2816 sc1
	s_waitcnt vmcnt(0)
	v_add_u32_e32 v10, -1, v2
	v_and_b32_e32 v10, v10, v2
	v_add_u32_e32 v11, -1, v3
	v_and_or_b32 v10, v11, v3, v10
	v_add_u32_e32 v11, -1, v4
	v_and_or_b32 v10, v11, v4, v10
	v_add_u32_e32 v11, -1, v5
	v_and_or_b32 v10, v11, v5, v10
	v_add_u32_e32 v11, -1, v6
	v_and_or_b32 v10, v11, v6, v10
	v_add_u32_e32 v11, -1, v7
	v_and_or_b32 v10, v11, v7, v10
	v_add_u32_e32 v11, -1, v8
	v_and_or_b32 v10, v11, v8, v10
	v_add_u32_e32 v11, -1, v9
	v_and_or_b32 v10, v11, v9, v10
	v_min_u32_e32 v11, v2, v3
	v_min3_u32 v11, v11, v4, v5
	v_min3_u32 v11, v11, v6, v7
	v_min3_u32 v11, v11, v8, v9
	v_cmp_eq_u32_e32 vcc, 0, v10
	v_mov_b32_e32 v2, 2
	s_nop 0
	v_cndmask_b32_e64 v2, v2, 1, vcc
	v_cmp_eq_u32_e32 vcc, 0, v11
	s_nop 1
	v_cndmask_b32_e64 v2, v2, 2, vcc
	ds_write_b32 v1, v2
	s_nop 0
	v_readfirstlane_b32 s101, v2
.Lbar_have_flag:
	s_cmp_eq_u32 s101, 1
	s_cbranch_scc0 .Lbar_global
	s_waitcnt lgkmcnt(0)
	s_branch .LBB0_752
.Lbar_global:
	buffer_wbl2 sc1
	s_waitcnt lgkmcnt(0)
	s_waitcnt vmcnt(0)
	v_mbcnt_lo_u32_b32 v1, s4, 0
	v_mbcnt_hi_u32_b32 v1, s5, v1
	v_cmp_eq_u32_e32 vcc, 0, v1
	s_and_saveexec_b64 s[10:11], vcc
	s_cbranch_execz .LBB0_738
	s_bcnt1_i32_b64 s4, s[4:5]
	v_mov_b32_e32 v2, s4
	v_readlane_b32 s4, v253, 48
	v_readlane_b32 s5, v253, 49
	s_nop 4
	global_atomic_add v2, v197, v2, s[4:5] sc0
